# t10 + in-proj plain/SiLU epilogue: accumulator copies removed (SiLU applied in place, cvt reads accumulators; s_nop keeps the store-data WAR distance)
# baseline (speedup 1.0000x reference)
; __device__ __forceinline__ unsigned cvt_pk_bf16(float lo, float hi) { f32x2_t v = {lo, hi}; bf16x2_t r = __builtin_convertvector(v, bf16x2_t); return __builtin_bit_cast(unsigned, r); }
; __device__ __forceinline__ float sigmoidf_(float v) { return __builtin_amdgcn_rcpf(1.0f + __builtin_amdgcn_exp2f(-1.4426950408889634f * v)); }
;     __device__ __forceinline__ void operator()(const f32x4 (&acc)[2][2][4][2], const Unit& u, int wr, int wc, int fr, int fq) const {
;     ...
; #pragma unroll
;         for (int ai = 0; ai < 2; ++ai)
; #pragma unroll
;             for (int m = 0; m < 4; ++m) { bf16_t* rowp = O + (size_t)(row0 + ai * HALF + m * 16) * NIN + col0;
; #pragma unroll
;                 for (int bj = 0; bj < 2; ++bj) { f32x4 v0 = acc[ai][bj][m][0], v1 = acc[ai][bj][m][1];
;                     if (mode != 0) {
; #pragma unroll
;                         for (int j = 0; j < 4; ++j) { v0[j] *= sigmoidf_(v0[j]); v1[j] *= sigmoidf_(v1[j]); }
;                     }
;                     u32x4 w; w.x = cvt_pk_bf16(v0[0], v0[1]); w.y = cvt_pk_bf16(v0[2], v0[3]); w.z = cvt_pk_bf16(v1[0], v1[1]); w.w = cvt_pk_bf16(v1[2], v1[3]);
;                     *(u32x4*)(rowp + bj * HALF) = w; } }
.LBB0_353:
	s_cmp_gt_i32 s46, 35
	s_cselect_b64 s[2:3], -1, 0
	s_and_b64 vcc, exec, s[2:3]
	s_cbranch_vccz .LBB0_355
	v_mul_f32_e32 v129, 0xbfb8aa3b, v120
	v_mul_f32_e32 v130, 0xbfb8aa3b, v125
	v_exp_f32_e32 v129, v129
	v_exp_f32_e32 v130, v130
	v_mul_f32_e32 v131, 0xbfb8aa3b, v126
	v_mul_f32_e32 v133, 0xbfb8aa3b, v122
	v_add_f32_e32 v129, 1.0, v129
	v_rcp_f32_e32 v132, v129
	v_add_f32_e32 v129, 1.0, v130
	v_mul_f32_e32 v130, 0xbfb8aa3b, v121
	v_exp_f32_e32 v130, v130
	v_exp_f32_e32 v131, v131
	v_exp_f32_e32 v133, v133
	v_mul_f32_e32 v128, 0xbfb8aa3b, v124
	v_add_f32_e32 v137, 1.0, v130
	v_add_f32_e32 v130, 1.0, v131
	v_add_f32_e32 v131, 1.0, v133
	v_mul_f32_e32 v133, 0xbfb8aa3b, v127
	v_mul_f32_e32 v134, 0xbfb8aa3b, v123
	v_exp_f32_e32 v128, v128
	v_exp_f32_e32 v133, v133
	v_exp_f32_e32 v135, v134
	v_rcp_f32_e32 v134, v131
	v_add_f32_e32 v128, 1.0, v128
	v_add_f32_e32 v131, 1.0, v133
	v_add_f32_e32 v133, 1.0, v135
	v_rcp_f32_e32 v128, v128
	v_rcp_f32_e32 v129, v129
	v_rcp_f32_e32 v130, v130
	v_rcp_f32_e32 v131, v131
	v_rcp_f32_e32 v135, v133
	v_rcp_f32_e32 v133, v137
	v_pk_mul_f32 v[124:125], v[124:125], v[128:129]
	v_pk_mul_f32 v[126:127], v[126:127], v[130:131]
	v_pk_mul_f32 v[122:123], v[122:123], v[134:135]
	v_pk_mul_f32 v[120:121], v[120:121], v[132:133]
.LBB0_355:
	s_lshl_b32 s11, s44, 8
	s_add_i32 s11, s11, s54
	v_add_u32_e32 v141, s11, v154
	v_mov_b64_e32 v[138:139], s[4:5]
	v_ashrrev_i32_e32 v137, 31, v136
	v_mad_i64_i32 v[138:139], s[20:21], v141, s14, v[138:139]
	v_lshl_add_u64 v[138:139], v[136:137], 1, v[138:139]
	v_cvt_pk_bf16_f32 v128, v124, v125
	v_cvt_pk_bf16_f32 v129, v126, v127
	v_cvt_pk_bf16_f32 v130, v120, v121
	v_cvt_pk_bf16_f32 v131, v122, v123
	global_store_dwordx4 v[138:139], v[128:131], off sc1 nt
	s_nop 0
	s_andn2_b64 vcc, exec, s[2:3]
	v_cndmask_b32_e64 v128, 0, 1, s[2:3]
	v_cmp_ne_u32_e64 s[38:39], 1, v128
	s_cbranch_vccnz .LBB0_357
	v_mul_f32_e32 v129, 0xbfb8aa3b, v112
	v_mul_f32_e32 v130, 0xbfb8aa3b, v117
	v_exp_f32_e32 v129, v129
	v_exp_f32_e32 v130, v130
	v_mul_f32_e32 v131, 0xbfb8aa3b, v118
	v_mul_f32_e32 v133, 0xbfb8aa3b, v114
	v_add_f32_e32 v129, 1.0, v129
	v_rcp_f32_e32 v132, v129
	v_add_f32_e32 v129, 1.0, v130
	v_mul_f32_e32 v130, 0xbfb8aa3b, v113
	v_exp_f32_e32 v130, v130
	v_exp_f32_e32 v131, v131
	v_exp_f32_e32 v133, v133
	v_mul_f32_e32 v128, 0xbfb8aa3b, v116
	v_add_f32_e32 v142, 1.0, v130
	v_add_f32_e32 v130, 1.0, v131
	v_add_f32_e32 v131, 1.0, v133
	v_mul_f32_e32 v133, 0xbfb8aa3b, v119
	v_mul_f32_e32 v134, 0xbfb8aa3b, v115
	v_exp_f32_e32 v128, v128
	v_exp_f32_e32 v133, v133
	v_exp_f32_e32 v135, v134
	v_rcp_f32_e32 v134, v131
	v_add_f32_e32 v128, 1.0, v128
	v_add_f32_e32 v131, 1.0, v133
	v_add_f32_e32 v133, 1.0, v135
	v_rcp_f32_e32 v128, v128
	v_rcp_f32_e32 v129, v129
	v_rcp_f32_e32 v130, v130
	v_rcp_f32_e32 v131, v131
	v_rcp_f32_e32 v135, v133
	v_rcp_f32_e32 v133, v142
	v_pk_mul_f32 v[116:117], v[116:117], v[128:129]
	v_pk_mul_f32 v[118:119], v[118:119], v[130:131]
	v_pk_mul_f32 v[114:115], v[114:115], v[134:135]
	v_pk_mul_f32 v[112:113], v[112:113], v[132:133]
.LBB0_357:
	v_cvt_pk_bf16_f32 v128, v116, v117
	v_cvt_pk_bf16_f32 v129, v118, v119
	v_cvt_pk_bf16_f32 v130, v112, v113
	v_cvt_pk_bf16_f32 v131, v114, v115
	global_store_dwordx4 v[138:139], v[128:131], off offset:256 sc1 nt
	s_nop 0
	s_and_b64 vcc, exec, s[38:39]
	s_cbranch_vccnz .LBB0_359
	v_mul_f32_e32 v129, 0xbfb8aa3b, v104
	v_mul_f32_e32 v130, 0xbfb8aa3b, v109
	v_exp_f32_e32 v129, v129
	v_exp_f32_e32 v130, v130
	v_mul_f32_e32 v131, 0xbfb8aa3b, v110
	v_mul_f32_e32 v133, 0xbfb8aa3b, v106
	v_add_f32_e32 v129, 1.0, v129
	v_rcp_f32_e32 v132, v129
	v_add_f32_e32 v129, 1.0, v130
	v_mul_f32_e32 v130, 0xbfb8aa3b, v105
	v_exp_f32_e32 v130, v130
	v_exp_f32_e32 v131, v131
	v_exp_f32_e32 v133, v133
	v_mul_f32_e32 v128, 0xbfb8aa3b, v108
	v_add_f32_e32 v138, 1.0, v130
	v_add_f32_e32 v130, 1.0, v131
	v_add_f32_e32 v131, 1.0, v133
	v_mul_f32_e32 v133, 0xbfb8aa3b, v111
	v_mul_f32_e32 v134, 0xbfb8aa3b, v107
	v_exp_f32_e32 v128, v128
	v_exp_f32_e32 v133, v133
	v_exp_f32_e32 v135, v134
	v_rcp_f32_e32 v134, v131
	v_add_f32_e32 v128, 1.0, v128
	v_add_f32_e32 v131, 1.0, v133
	v_add_f32_e32 v133, 1.0, v135
	v_rcp_f32_e32 v128, v128
	v_rcp_f32_e32 v129, v129
	v_rcp_f32_e32 v130, v130
	v_rcp_f32_e32 v131, v131
	v_rcp_f32_e32 v135, v133
	v_rcp_f32_e32 v133, v138
	v_pk_mul_f32 v[108:109], v[108:109], v[128:129]
	v_pk_mul_f32 v[110:111], v[110:111], v[130:131]
	v_pk_mul_f32 v[106:107], v[106:107], v[134:135]
	v_pk_mul_f32 v[104:105], v[104:105], v[132:133]
.LBB0_359:
	v_add_u32_e32 v142, 16, v141
	v_mov_b64_e32 v[138:139], s[4:5]
	v_mad_i64_i32 v[138:139], s[2:3], v142, s14, v[138:139]
	v_lshl_add_u64 v[138:139], v[136:137], 1, v[138:139]
	v_cvt_pk_bf16_f32 v128, v108, v109
	v_cvt_pk_bf16_f32 v129, v110, v111
	v_cvt_pk_bf16_f32 v130, v104, v105
	v_cvt_pk_bf16_f32 v131, v106, v107
	global_store_dwordx4 v[138:139], v[128:131], off sc1 nt
	s_nop 0
	s_and_b64 vcc, exec, s[38:39]
	s_cbranch_vccnz .LBB0_361
	v_mul_f32_e32 v129, 0xbfb8aa3b, v96
	v_mul_f32_e32 v130, 0xbfb8aa3b, v101
	v_exp_f32_e32 v129, v129
	v_exp_f32_e32 v130, v130
	v_mul_f32_e32 v131, 0xbfb8aa3b, v102
	v_mul_f32_e32 v133, 0xbfb8aa3b, v98
	v_add_f32_e32 v129, 1.0, v129
	v_rcp_f32_e32 v132, v129
	v_add_f32_e32 v129, 1.0, v130
	v_mul_f32_e32 v130, 0xbfb8aa3b, v97
	v_exp_f32_e32 v130, v130
	v_exp_f32_e32 v131, v131
	v_exp_f32_e32 v133, v133
	v_mul_f32_e32 v128, 0xbfb8aa3b, v100
	v_add_f32_e32 v142, 1.0, v130
	v_add_f32_e32 v130, 1.0, v131
	v_add_f32_e32 v131, 1.0, v133
	v_mul_f32_e32 v133, 0xbfb8aa3b, v103
	v_mul_f32_e32 v134, 0xbfb8aa3b, v99
	v_exp_f32_e32 v128, v128
	v_exp_f32_e32 v133, v133
	v_exp_f32_e32 v135, v134
	v_rcp_f32_e32 v134, v131
	v_add_f32_e32 v128, 1.0, v128
	v_add_f32_e32 v131, 1.0, v133
	v_add_f32_e32 v133, 1.0, v135
	v_rcp_f32_e32 v128, v128
	v_rcp_f32_e32 v129, v129
	v_rcp_f32_e32 v130, v130
	v_rcp_f32_e32 v131, v131
	v_rcp_f32_e32 v135, v133
	v_rcp_f32_e32 v133, v142
	v_pk_mul_f32 v[100:101], v[100:101], v[128:129]
	v_pk_mul_f32 v[102:103], v[102:103], v[130:131]
	v_pk_mul_f32 v[98:99], v[98:99], v[134:135]
	v_pk_mul_f32 v[96:97], v[96:97], v[132:133]
; __device__ __forceinline__ unsigned cvt_pk_bf16(float lo, float hi) { f32x2_t v = {lo, hi}; bf16x2_t r = __builtin_convertvector(v, bf16x2_t); return __builtin_bit_cast(unsigned, r); }
; __device__ __forceinline__ float sigmoidf_(float v) { return __builtin_amdgcn_rcpf(1.0f + __builtin_amdgcn_exp2f(-1.4426950408889634f * v)); }
;     __device__ __forceinline__ void operator()(const f32x4 (&acc)[2][2][4][2], const Unit& u, int wr, int wc, int fr, int fq) const {
;     ...
; #pragma unroll
;         for (int ai = 0; ai < 2; ++ai)
; #pragma unroll
;             for (int m = 0; m < 4; ++m) { bf16_t* rowp = O + (size_t)(row0 + ai * HALF + m * 16) * NIN + col0;
; #pragma unroll
;                 for (int bj = 0; bj < 2; ++bj) { f32x4 v0 = acc[ai][bj][m][0], v1 = acc[ai][bj][m][1];
;                     if (mode != 0) {
; #pragma unroll
;                         for (int j = 0; j < 4; ++j) { v0[j] *= sigmoidf_(v0[j]); v1[j] *= sigmoidf_(v1[j]); }
;                     }
;                     u32x4 w; w.x = cvt_pk_bf16(v0[0], v0[1]); w.y = cvt_pk_bf16(v0[2], v0[3]); w.z = cvt_pk_bf16(v1[0], v1[1]); w.w = cvt_pk_bf16(v1[2], v1[3]);
;                     *(u32x4*)(rowp + bj * HALF) = w; } }
.LBB0_361:
	v_cvt_pk_bf16_f32 v128, v100, v101
	v_cvt_pk_bf16_f32 v129, v102, v103
	v_cvt_pk_bf16_f32 v130, v96, v97
	v_cvt_pk_bf16_f32 v131, v98, v99
	global_store_dwordx4 v[138:139], v[128:131], off offset:256 sc1 nt
	s_nop 0
	s_and_b64 vcc, exec, s[38:39]
	s_cbranch_vccnz .LBB0_363
	v_mul_f32_e32 v129, 0xbfb8aa3b, v88
	v_mul_f32_e32 v130, 0xbfb8aa3b, v93
	v_exp_f32_e32 v129, v129
	v_exp_f32_e32 v130, v130
	v_mul_f32_e32 v131, 0xbfb8aa3b, v94
	v_mul_f32_e32 v133, 0xbfb8aa3b, v90
	v_add_f32_e32 v129, 1.0, v129
	v_rcp_f32_e32 v132, v129
	v_add_f32_e32 v129, 1.0, v130
	v_mul_f32_e32 v130, 0xbfb8aa3b, v89
	v_exp_f32_e32 v130, v130
	v_exp_f32_e32 v131, v131
	v_exp_f32_e32 v133, v133
	v_mul_f32_e32 v128, 0xbfb8aa3b, v92
	v_add_f32_e32 v138, 1.0, v130
	v_add_f32_e32 v130, 1.0, v131
	v_add_f32_e32 v131, 1.0, v133
	v_mul_f32_e32 v133, 0xbfb8aa3b, v95
	v_mul_f32_e32 v134, 0xbfb8aa3b, v91
	v_exp_f32_e32 v128, v128
	v_exp_f32_e32 v133, v133
	v_exp_f32_e32 v135, v134
	v_rcp_f32_e32 v134, v131
	v_add_f32_e32 v128, 1.0, v128
	v_add_f32_e32 v131, 1.0, v133
	v_add_f32_e32 v133, 1.0, v135
	v_rcp_f32_e32 v128, v128
	v_rcp_f32_e32 v129, v129
	v_rcp_f32_e32 v130, v130
	v_rcp_f32_e32 v131, v131
	v_rcp_f32_e32 v135, v133
	v_rcp_f32_e32 v133, v138
	v_pk_mul_f32 v[92:93], v[92:93], v[128:129]
	v_pk_mul_f32 v[94:95], v[94:95], v[130:131]
	v_pk_mul_f32 v[90:91], v[90:91], v[134:135]
	v_pk_mul_f32 v[88:89], v[88:89], v[132:133]
.LBB0_363:
	v_add_u32_e32 v142, 32, v141
	v_mov_b64_e32 v[138:139], s[4:5]
	v_mad_i64_i32 v[138:139], s[2:3], v142, s14, v[138:139]
	v_lshl_add_u64 v[138:139], v[136:137], 1, v[138:139]
	v_cvt_pk_bf16_f32 v128, v92, v93
	v_cvt_pk_bf16_f32 v129, v94, v95
	v_cvt_pk_bf16_f32 v130, v88, v89
	v_cvt_pk_bf16_f32 v131, v90, v91
	global_store_dwordx4 v[138:139], v[128:131], off sc1 nt
	s_nop 0
	s_and_b64 vcc, exec, s[38:39]
	s_cbranch_vccnz .LBB0_365
	v_mul_f32_e32 v129, 0xbfb8aa3b, v80
	v_mul_f32_e32 v130, 0xbfb8aa3b, v85
	v_exp_f32_e32 v129, v129
	v_exp_f32_e32 v130, v130
	v_mul_f32_e32 v131, 0xbfb8aa3b, v86
	v_mul_f32_e32 v133, 0xbfb8aa3b, v82
	v_add_f32_e32 v129, 1.0, v129
	v_rcp_f32_e32 v132, v129
	v_add_f32_e32 v129, 1.0, v130
	v_mul_f32_e32 v130, 0xbfb8aa3b, v81
	v_exp_f32_e32 v130, v130
	v_exp_f32_e32 v131, v131
	v_exp_f32_e32 v133, v133
	v_mul_f32_e32 v128, 0xbfb8aa3b, v84
	v_add_f32_e32 v142, 1.0, v130
	v_add_f32_e32 v130, 1.0, v131
	v_add_f32_e32 v131, 1.0, v133
	v_mul_f32_e32 v133, 0xbfb8aa3b, v87
	v_mul_f32_e32 v134, 0xbfb8aa3b, v83
	v_exp_f32_e32 v128, v128
	v_exp_f32_e32 v133, v133
	v_exp_f32_e32 v135, v134
	v_rcp_f32_e32 v134, v131
	v_add_f32_e32 v128, 1.0, v128
	v_add_f32_e32 v131, 1.0, v133
	v_add_f32_e32 v133, 1.0, v135
	v_rcp_f32_e32 v128, v128
	v_rcp_f32_e32 v129, v129
	v_rcp_f32_e32 v130, v130
	v_rcp_f32_e32 v131, v131
	v_rcp_f32_e32 v135, v133
	v_rcp_f32_e32 v133, v142
	v_pk_mul_f32 v[84:85], v[84:85], v[128:129]
	v_pk_mul_f32 v[86:87], v[86:87], v[130:131]
	v_pk_mul_f32 v[82:83], v[82:83], v[134:135]
	v_pk_mul_f32 v[80:81], v[80:81], v[132:133]
.LBB0_365:
	v_cvt_pk_bf16_f32 v128, v84, v85
	v_cvt_pk_bf16_f32 v129, v86, v87
	v_cvt_pk_bf16_f32 v130, v80, v81
	v_cvt_pk_bf16_f32 v131, v82, v83
	global_store_dwordx4 v[138:139], v[128:131], off offset:256 sc1 nt
	s_nop 0
	s_and_b64 vcc, exec, s[38:39]
	s_cbranch_vccnz .LBB0_367
	v_mul_f32_e32 v129, 0xbfb8aa3b, v72
	v_mul_f32_e32 v130, 0xbfb8aa3b, v77
	v_exp_f32_e32 v129, v129
	v_exp_f32_e32 v130, v130
	v_mul_f32_e32 v131, 0xbfb8aa3b, v78
	v_mul_f32_e32 v133, 0xbfb8aa3b, v74
	v_add_f32_e32 v129, 1.0, v129
	v_rcp_f32_e32 v132, v129
	v_add_f32_e32 v129, 1.0, v130
	v_mul_f32_e32 v130, 0xbfb8aa3b, v73
	v_exp_f32_e32 v130, v130
	v_exp_f32_e32 v131, v131
	v_exp_f32_e32 v133, v133
	v_mul_f32_e32 v128, 0xbfb8aa3b, v76
	v_add_f32_e32 v138, 1.0, v130
	v_add_f32_e32 v130, 1.0, v131
	v_add_f32_e32 v131, 1.0, v133
	v_mul_f32_e32 v133, 0xbfb8aa3b, v79
	v_mul_f32_e32 v134, 0xbfb8aa3b, v75
	v_exp_f32_e32 v128, v128
	v_exp_f32_e32 v133, v133
	v_exp_f32_e32 v135, v134
	v_rcp_f32_e32 v134, v131
	v_add_f32_e32 v128, 1.0, v128
	v_add_f32_e32 v131, 1.0, v133
	v_add_f32_e32 v133, 1.0, v135
	v_rcp_f32_e32 v128, v128
	v_rcp_f32_e32 v129, v129
	v_rcp_f32_e32 v130, v130
	v_rcp_f32_e32 v131, v131
	v_rcp_f32_e32 v135, v133
	v_rcp_f32_e32 v133, v138
	v_pk_mul_f32 v[76:77], v[76:77], v[128:129]
	v_pk_mul_f32 v[78:79], v[78:79], v[130:131]
	v_pk_mul_f32 v[74:75], v[74:75], v[134:135]
	v_pk_mul_f32 v[72:73], v[72:73], v[132:133]
.LBB0_367:
	v_add_u32_e32 v142, 48, v141
	v_mov_b64_e32 v[138:139], s[4:5]
	v_mad_i64_i32 v[138:139], s[2:3], v142, s14, v[138:139]
	v_lshl_add_u64 v[138:139], v[136:137], 1, v[138:139]
	v_cvt_pk_bf16_f32 v128, v76, v77
	v_cvt_pk_bf16_f32 v129, v78, v79
	v_cvt_pk_bf16_f32 v130, v72, v73
	v_cvt_pk_bf16_f32 v131, v74, v75
	global_store_dwordx4 v[138:139], v[128:131], off sc1 nt
	s_nop 0
	s_and_b64 vcc, exec, s[38:39]
	s_cbranch_vccnz .LBB0_369
	v_mul_f32_e32 v129, 0xbfb8aa3b, v64
	v_mul_f32_e32 v130, 0xbfb8aa3b, v69
	v_exp_f32_e32 v129, v129
	v_exp_f32_e32 v130, v130
	v_mul_f32_e32 v131, 0xbfb8aa3b, v70
	v_mul_f32_e32 v133, 0xbfb8aa3b, v66
	v_add_f32_e32 v129, 1.0, v129
	v_rcp_f32_e32 v132, v129
	v_add_f32_e32 v129, 1.0, v130
	v_mul_f32_e32 v130, 0xbfb8aa3b, v65
	v_exp_f32_e32 v130, v130
	v_exp_f32_e32 v131, v131
	v_exp_f32_e32 v133, v133
	v_mul_f32_e32 v128, 0xbfb8aa3b, v68
	v_add_f32_e32 v142, 1.0, v130
	v_add_f32_e32 v130, 1.0, v131
	v_add_f32_e32 v131, 1.0, v133
	v_mul_f32_e32 v133, 0xbfb8aa3b, v71
	v_mul_f32_e32 v134, 0xbfb8aa3b, v67
	v_exp_f32_e32 v128, v128
	v_exp_f32_e32 v133, v133
	v_exp_f32_e32 v135, v134
	v_rcp_f32_e32 v134, v131
	v_add_f32_e32 v128, 1.0, v128
	v_add_f32_e32 v131, 1.0, v133
	v_add_f32_e32 v133, 1.0, v135
	v_rcp_f32_e32 v128, v128
	v_rcp_f32_e32 v129, v129
	v_rcp_f32_e32 v130, v130
	v_rcp_f32_e32 v131, v131
	v_rcp_f32_e32 v135, v133
	v_rcp_f32_e32 v133, v142
	v_pk_mul_f32 v[68:69], v[68:69], v[128:129]
	v_pk_mul_f32 v[70:71], v[70:71], v[130:131]
	v_pk_mul_f32 v[66:67], v[66:67], v[134:135]
	v_pk_mul_f32 v[64:65], v[64:65], v[132:133]
; __device__ __forceinline__ unsigned cvt_pk_bf16(float lo, float hi) { f32x2_t v = {lo, hi}; bf16x2_t r = __builtin_convertvector(v, bf16x2_t); return __builtin_bit_cast(unsigned, r); }
; __device__ __forceinline__ float sigmoidf_(float v) { return __builtin_amdgcn_rcpf(1.0f + __builtin_amdgcn_exp2f(-1.4426950408889634f * v)); }
;     __device__ __forceinline__ void operator()(const f32x4 (&acc)[2][2][4][2], const Unit& u, int wr, int wc, int fr, int fq) const {
;     ...
; #pragma unroll
;         for (int ai = 0; ai < 2; ++ai)
; #pragma unroll
;             for (int m = 0; m < 4; ++m) { bf16_t* rowp = O + (size_t)(row0 + ai * HALF + m * 16) * NIN + col0;
; #pragma unroll
;                 for (int bj = 0; bj < 2; ++bj) { f32x4 v0 = acc[ai][bj][m][0], v1 = acc[ai][bj][m][1];
;                     if (mode != 0) {
; #pragma unroll
;                         for (int j = 0; j < 4; ++j) { v0[j] *= sigmoidf_(v0[j]); v1[j] *= sigmoidf_(v1[j]); }
;                     }
;                     u32x4 w; w.x = cvt_pk_bf16(v0[0], v0[1]); w.y = cvt_pk_bf16(v0[2], v0[3]); w.z = cvt_pk_bf16(v1[0], v1[1]); w.w = cvt_pk_bf16(v1[2], v1[3]);
;                     *(u32x4*)(rowp + bj * HALF) = w; } }
.LBB0_369:
	v_cvt_pk_bf16_f32 v128, v68, v69
	v_cvt_pk_bf16_f32 v129, v70, v71
	v_cvt_pk_bf16_f32 v130, v64, v65
	v_cvt_pk_bf16_f32 v131, v66, v67
	global_store_dwordx4 v[138:139], v[128:131], off offset:256 sc1 nt
	s_nop 0
	s_and_b64 vcc, exec, s[38:39]
	s_cbranch_vccnz .LBB0_371
	v_mul_f32_e32 v129, 0xbfb8aa3b, v56
	v_mul_f32_e32 v130, 0xbfb8aa3b, v61
	v_exp_f32_e32 v129, v129
	v_exp_f32_e32 v130, v130
	v_mul_f32_e32 v131, 0xbfb8aa3b, v62
	v_mul_f32_e32 v133, 0xbfb8aa3b, v58
	v_add_f32_e32 v129, 1.0, v129
	v_rcp_f32_e32 v132, v129
	v_add_f32_e32 v129, 1.0, v130
	v_mul_f32_e32 v130, 0xbfb8aa3b, v57
	v_exp_f32_e32 v130, v130
	v_exp_f32_e32 v131, v131
	v_exp_f32_e32 v133, v133
	v_mul_f32_e32 v128, 0xbfb8aa3b, v60
	v_add_f32_e32 v138, 1.0, v130
	v_add_f32_e32 v130, 1.0, v131
	v_add_f32_e32 v131, 1.0, v133
	v_mul_f32_e32 v133, 0xbfb8aa3b, v63
	v_mul_f32_e32 v134, 0xbfb8aa3b, v59
	v_exp_f32_e32 v128, v128
	v_exp_f32_e32 v133, v133
	v_exp_f32_e32 v135, v134
	v_rcp_f32_e32 v134, v131
	v_add_f32_e32 v128, 1.0, v128
	v_add_f32_e32 v131, 1.0, v133
	v_add_f32_e32 v133, 1.0, v135
	v_rcp_f32_e32 v128, v128
	v_rcp_f32_e32 v129, v129
	v_rcp_f32_e32 v130, v130
	v_rcp_f32_e32 v131, v131
	v_rcp_f32_e32 v135, v133
	v_rcp_f32_e32 v133, v138
	v_pk_mul_f32 v[60:61], v[60:61], v[128:129]
	v_pk_mul_f32 v[62:63], v[62:63], v[130:131]
	v_pk_mul_f32 v[58:59], v[58:59], v[134:135]
	v_pk_mul_f32 v[56:57], v[56:57], v[132:133]
.LBB0_371:
	v_add_u32_e32 v142, 0x80, v141
	v_mov_b64_e32 v[138:139], s[4:5]
	v_mad_i64_i32 v[138:139], s[2:3], v142, s14, v[138:139]
	v_lshl_add_u64 v[138:139], v[136:137], 1, v[138:139]
	v_cvt_pk_bf16_f32 v128, v60, v61
	v_cvt_pk_bf16_f32 v129, v62, v63
	v_cvt_pk_bf16_f32 v130, v56, v57
	v_cvt_pk_bf16_f32 v131, v58, v59
	global_store_dwordx4 v[138:139], v[128:131], off sc1 nt
	s_nop 0
	s_and_b64 vcc, exec, s[38:39]
	s_cbranch_vccnz .LBB0_373
	v_mul_f32_e32 v129, 0xbfb8aa3b, v48
	v_mul_f32_e32 v130, 0xbfb8aa3b, v53
	v_exp_f32_e32 v129, v129
	v_exp_f32_e32 v130, v130
	v_mul_f32_e32 v131, 0xbfb8aa3b, v54
	v_mul_f32_e32 v133, 0xbfb8aa3b, v50
	v_add_f32_e32 v129, 1.0, v129
	v_rcp_f32_e32 v132, v129
	v_add_f32_e32 v129, 1.0, v130
	v_mul_f32_e32 v130, 0xbfb8aa3b, v49
	v_exp_f32_e32 v130, v130
	v_exp_f32_e32 v131, v131
	v_exp_f32_e32 v133, v133
	v_mul_f32_e32 v128, 0xbfb8aa3b, v52
	v_add_f32_e32 v142, 1.0, v130
	v_add_f32_e32 v130, 1.0, v131
	v_add_f32_e32 v131, 1.0, v133
	v_mul_f32_e32 v133, 0xbfb8aa3b, v55
	v_mul_f32_e32 v134, 0xbfb8aa3b, v51
	v_exp_f32_e32 v128, v128
	v_exp_f32_e32 v133, v133
	v_exp_f32_e32 v135, v134
	v_rcp_f32_e32 v134, v131
	v_add_f32_e32 v128, 1.0, v128
	v_add_f32_e32 v131, 1.0, v133
	v_add_f32_e32 v133, 1.0, v135
	v_rcp_f32_e32 v128, v128
	v_rcp_f32_e32 v129, v129
	v_rcp_f32_e32 v130, v130
	v_rcp_f32_e32 v131, v131
	v_rcp_f32_e32 v135, v133
	v_rcp_f32_e32 v133, v142
	v_pk_mul_f32 v[52:53], v[52:53], v[128:129]
	v_pk_mul_f32 v[54:55], v[54:55], v[130:131]
	v_pk_mul_f32 v[50:51], v[50:51], v[134:135]
	v_pk_mul_f32 v[48:49], v[48:49], v[132:133]
.LBB0_373:
	v_cvt_pk_bf16_f32 v128, v52, v53
	v_cvt_pk_bf16_f32 v129, v54, v55
	v_cvt_pk_bf16_f32 v130, v48, v49
	v_cvt_pk_bf16_f32 v131, v50, v51
	global_store_dwordx4 v[138:139], v[128:131], off offset:256 sc1 nt
	s_nop 0
	s_and_b64 vcc, exec, s[38:39]
	s_cbranch_vccnz .LBB0_375
	v_mul_f32_e32 v129, 0xbfb8aa3b, v40
	v_mul_f32_e32 v130, 0xbfb8aa3b, v45
	v_exp_f32_e32 v129, v129
	v_exp_f32_e32 v130, v130
	v_mul_f32_e32 v131, 0xbfb8aa3b, v46
	v_mul_f32_e32 v133, 0xbfb8aa3b, v42
	v_add_f32_e32 v129, 1.0, v129
	v_rcp_f32_e32 v132, v129
	v_add_f32_e32 v129, 1.0, v130
	v_mul_f32_e32 v130, 0xbfb8aa3b, v41
	v_exp_f32_e32 v130, v130
	v_exp_f32_e32 v131, v131
	v_exp_f32_e32 v133, v133
	v_mul_f32_e32 v128, 0xbfb8aa3b, v44
	v_add_f32_e32 v138, 1.0, v130
	v_add_f32_e32 v130, 1.0, v131
	v_add_f32_e32 v131, 1.0, v133
	v_mul_f32_e32 v133, 0xbfb8aa3b, v47
	v_mul_f32_e32 v134, 0xbfb8aa3b, v43
	v_exp_f32_e32 v128, v128
	v_exp_f32_e32 v133, v133
	v_exp_f32_e32 v135, v134
	v_rcp_f32_e32 v134, v131
	v_add_f32_e32 v128, 1.0, v128
	v_add_f32_e32 v131, 1.0, v133
	v_add_f32_e32 v133, 1.0, v135
	v_rcp_f32_e32 v128, v128
	v_rcp_f32_e32 v129, v129
	v_rcp_f32_e32 v130, v130
	v_rcp_f32_e32 v131, v131
	v_rcp_f32_e32 v135, v133
	v_rcp_f32_e32 v133, v138
	v_pk_mul_f32 v[44:45], v[44:45], v[128:129]
	v_pk_mul_f32 v[46:47], v[46:47], v[130:131]
	v_pk_mul_f32 v[42:43], v[42:43], v[134:135]
	v_pk_mul_f32 v[40:41], v[40:41], v[132:133]
.LBB0_375:
	v_add_u32_e32 v142, 0x90, v141
	v_mov_b64_e32 v[138:139], s[4:5]
	v_mad_i64_i32 v[138:139], s[2:3], v142, s14, v[138:139]
	v_lshl_add_u64 v[138:139], v[136:137], 1, v[138:139]
	v_cvt_pk_bf16_f32 v128, v44, v45
	v_cvt_pk_bf16_f32 v129, v46, v47
	v_cvt_pk_bf16_f32 v130, v40, v41
	v_cvt_pk_bf16_f32 v131, v42, v43
	global_store_dwordx4 v[138:139], v[128:131], off sc1 nt
	s_nop 0
	s_and_b64 vcc, exec, s[38:39]
	s_cbranch_vccnz .LBB0_377
	v_mul_f32_e32 v129, 0xbfb8aa3b, v32
	v_mul_f32_e32 v130, 0xbfb8aa3b, v37
	v_exp_f32_e32 v129, v129
	v_exp_f32_e32 v130, v130
	v_mul_f32_e32 v131, 0xbfb8aa3b, v38
	v_mul_f32_e32 v133, 0xbfb8aa3b, v34
	v_add_f32_e32 v129, 1.0, v129
	v_rcp_f32_e32 v132, v129
	v_add_f32_e32 v129, 1.0, v130
	v_mul_f32_e32 v130, 0xbfb8aa3b, v33
	v_exp_f32_e32 v130, v130
	v_exp_f32_e32 v131, v131
	v_exp_f32_e32 v133, v133
	v_mul_f32_e32 v128, 0xbfb8aa3b, v36
	v_add_f32_e32 v142, 1.0, v130
	v_add_f32_e32 v130, 1.0, v131
	v_add_f32_e32 v131, 1.0, v133
	v_mul_f32_e32 v133, 0xbfb8aa3b, v39
	v_mul_f32_e32 v134, 0xbfb8aa3b, v35
	v_exp_f32_e32 v128, v128
	v_exp_f32_e32 v133, v133
	v_exp_f32_e32 v135, v134
	v_rcp_f32_e32 v134, v131
	v_add_f32_e32 v128, 1.0, v128
	v_add_f32_e32 v131, 1.0, v133
	v_add_f32_e32 v133, 1.0, v135
	v_rcp_f32_e32 v128, v128
	v_rcp_f32_e32 v129, v129
	v_rcp_f32_e32 v130, v130
	v_rcp_f32_e32 v131, v131
	v_rcp_f32_e32 v135, v133
	v_rcp_f32_e32 v133, v142
	v_pk_mul_f32 v[36:37], v[36:37], v[128:129]
	v_pk_mul_f32 v[38:39], v[38:39], v[130:131]
	v_pk_mul_f32 v[34:35], v[34:35], v[134:135]
	v_pk_mul_f32 v[32:33], v[32:33], v[132:133]
; __device__ __forceinline__ unsigned cvt_pk_bf16(float lo, float hi) { f32x2_t v = {lo, hi}; bf16x2_t r = __builtin_convertvector(v, bf16x2_t); return __builtin_bit_cast(unsigned, r); }
; __device__ __forceinline__ float sigmoidf_(float v) { return __builtin_amdgcn_rcpf(1.0f + __builtin_amdgcn_exp2f(-1.4426950408889634f * v)); }
;     __device__ __forceinline__ void operator()(const f32x4 (&acc)[2][2][4][2], const Unit& u, int wr, int wc, int fr, int fq) const {
;     ...
; #pragma unroll
;         for (int ai = 0; ai < 2; ++ai)
; #pragma unroll
;             for (int m = 0; m < 4; ++m) { bf16_t* rowp = O + (size_t)(row0 + ai * HALF + m * 16) * NIN + col0;
; #pragma unroll
;                 for (int bj = 0; bj < 2; ++bj) { f32x4 v0 = acc[ai][bj][m][0], v1 = acc[ai][bj][m][1];
;                     if (mode != 0) {
; #pragma unroll
;                         for (int j = 0; j < 4; ++j) { v0[j] *= sigmoidf_(v0[j]); v1[j] *= sigmoidf_(v1[j]); }
;                     }
;                     u32x4 w; w.x = cvt_pk_bf16(v0[0], v0[1]); w.y = cvt_pk_bf16(v0[2], v0[3]); w.z = cvt_pk_bf16(v1[0], v1[1]); w.w = cvt_pk_bf16(v1[2], v1[3]);
;                     *(u32x4*)(rowp + bj * HALF) = w; } }
.LBB0_377:
	v_cvt_pk_bf16_f32 v128, v36, v37
	v_cvt_pk_bf16_f32 v129, v38, v39
	v_cvt_pk_bf16_f32 v130, v32, v33
	v_cvt_pk_bf16_f32 v131, v34, v35
	global_store_dwordx4 v[138:139], v[128:131], off offset:256 sc1 nt
	s_nop 0
	s_and_b64 vcc, exec, s[38:39]
	s_cbranch_vccnz .LBB0_379
	v_mul_f32_e32 v129, 0xbfb8aa3b, v24
	v_mul_f32_e32 v130, 0xbfb8aa3b, v29
	v_exp_f32_e32 v129, v129
	v_exp_f32_e32 v130, v130
	v_mul_f32_e32 v131, 0xbfb8aa3b, v30
	v_mul_f32_e32 v133, 0xbfb8aa3b, v26
	v_add_f32_e32 v129, 1.0, v129
	v_rcp_f32_e32 v132, v129
	v_add_f32_e32 v129, 1.0, v130
	v_mul_f32_e32 v130, 0xbfb8aa3b, v25
	v_exp_f32_e32 v130, v130
	v_exp_f32_e32 v131, v131
	v_exp_f32_e32 v133, v133
	v_mul_f32_e32 v128, 0xbfb8aa3b, v28
	v_add_f32_e32 v138, 1.0, v130
	v_add_f32_e32 v130, 1.0, v131
	v_add_f32_e32 v131, 1.0, v133
	v_mul_f32_e32 v133, 0xbfb8aa3b, v31
	v_mul_f32_e32 v134, 0xbfb8aa3b, v27
	v_exp_f32_e32 v128, v128
	v_exp_f32_e32 v133, v133
	v_exp_f32_e32 v135, v134
	v_rcp_f32_e32 v134, v131
	v_add_f32_e32 v128, 1.0, v128
	v_add_f32_e32 v131, 1.0, v133
	v_add_f32_e32 v133, 1.0, v135
	v_rcp_f32_e32 v128, v128
	v_rcp_f32_e32 v129, v129
	v_rcp_f32_e32 v130, v130
	v_rcp_f32_e32 v131, v131
	v_rcp_f32_e32 v135, v133
	v_rcp_f32_e32 v133, v138
	v_pk_mul_f32 v[28:29], v[28:29], v[128:129]
	v_pk_mul_f32 v[30:31], v[30:31], v[130:131]
	v_pk_mul_f32 v[26:27], v[26:27], v[134:135]
	v_pk_mul_f32 v[24:25], v[24:25], v[132:133]
.LBB0_379:
	v_add_u32_e32 v142, 0xa0, v141
	v_mov_b64_e32 v[138:139], s[4:5]
	v_mad_i64_i32 v[138:139], s[2:3], v142, s14, v[138:139]
	v_lshl_add_u64 v[138:139], v[136:137], 1, v[138:139]
	v_cvt_pk_bf16_f32 v128, v28, v29
	v_cvt_pk_bf16_f32 v129, v30, v31
	v_cvt_pk_bf16_f32 v130, v24, v25
	v_cvt_pk_bf16_f32 v131, v26, v27
	global_store_dwordx4 v[138:139], v[128:131], off sc1 nt
	s_nop 0
	s_and_b64 vcc, exec, s[38:39]
	s_cbranch_vccnz .LBB0_381
	v_mul_f32_e32 v129, 0xbfb8aa3b, v16
	v_mul_f32_e32 v130, 0xbfb8aa3b, v21
	v_exp_f32_e32 v129, v129
	v_exp_f32_e32 v130, v130
	v_mul_f32_e32 v131, 0xbfb8aa3b, v22
	v_mul_f32_e32 v133, 0xbfb8aa3b, v18
	v_add_f32_e32 v129, 1.0, v129
	v_rcp_f32_e32 v132, v129
	v_add_f32_e32 v129, 1.0, v130
	v_mul_f32_e32 v130, 0xbfb8aa3b, v17
	v_exp_f32_e32 v130, v130
	v_exp_f32_e32 v131, v131
	v_exp_f32_e32 v133, v133
	v_mul_f32_e32 v128, 0xbfb8aa3b, v20
	v_add_f32_e32 v142, 1.0, v130
	v_add_f32_e32 v130, 1.0, v131
	v_add_f32_e32 v131, 1.0, v133
	v_mul_f32_e32 v133, 0xbfb8aa3b, v23
	v_mul_f32_e32 v134, 0xbfb8aa3b, v19
	v_exp_f32_e32 v128, v128
	v_exp_f32_e32 v133, v133
	v_exp_f32_e32 v135, v134
	v_rcp_f32_e32 v134, v131
	v_add_f32_e32 v128, 1.0, v128
	v_add_f32_e32 v131, 1.0, v133
	v_add_f32_e32 v133, 1.0, v135
	v_rcp_f32_e32 v128, v128
	v_rcp_f32_e32 v129, v129
	v_rcp_f32_e32 v130, v130
	v_rcp_f32_e32 v131, v131
	v_rcp_f32_e32 v135, v133
	v_rcp_f32_e32 v133, v142
	v_pk_mul_f32 v[20:21], v[20:21], v[128:129]
	v_pk_mul_f32 v[22:23], v[22:23], v[130:131]
	v_pk_mul_f32 v[18:19], v[18:19], v[134:135]
	v_pk_mul_f32 v[16:17], v[16:17], v[132:133]
.LBB0_381:
	v_cvt_pk_bf16_f32 v128, v20, v21
	v_cvt_pk_bf16_f32 v129, v22, v23
	v_cvt_pk_bf16_f32 v130, v16, v17
	v_cvt_pk_bf16_f32 v131, v18, v19
	global_store_dwordx4 v[138:139], v[128:131], off offset:256 sc1 nt
	s_nop 0
	s_and_b64 vcc, exec, s[38:39]
	s_cbranch_vccnz .LBB0_383
	v_mul_f32_e32 v129, 0xbfb8aa3b, v8
	v_mul_f32_e32 v130, 0xbfb8aa3b, v13
	v_exp_f32_e32 v129, v129
	v_exp_f32_e32 v130, v130
	v_mul_f32_e32 v131, 0xbfb8aa3b, v14
	v_mul_f32_e32 v133, 0xbfb8aa3b, v10
	v_add_f32_e32 v129, 1.0, v129
	v_rcp_f32_e32 v132, v129
	v_add_f32_e32 v129, 1.0, v130
	v_mul_f32_e32 v130, 0xbfb8aa3b, v9
	v_exp_f32_e32 v130, v130
	v_exp_f32_e32 v131, v131
	v_exp_f32_e32 v133, v133
	v_mul_f32_e32 v128, 0xbfb8aa3b, v12
	v_add_f32_e32 v138, 1.0, v130
	v_add_f32_e32 v130, 1.0, v131
	v_add_f32_e32 v131, 1.0, v133
	v_mul_f32_e32 v133, 0xbfb8aa3b, v15
	v_mul_f32_e32 v134, 0xbfb8aa3b, v11
	v_exp_f32_e32 v128, v128
	v_exp_f32_e32 v133, v133
	v_exp_f32_e32 v135, v134
	v_rcp_f32_e32 v134, v131
	v_add_f32_e32 v128, 1.0, v128
	v_add_f32_e32 v131, 1.0, v133
	v_add_f32_e32 v133, 1.0, v135
	v_rcp_f32_e32 v128, v128
	v_rcp_f32_e32 v129, v129
	v_rcp_f32_e32 v130, v130
	v_rcp_f32_e32 v131, v131
	v_rcp_f32_e32 v135, v133
	v_rcp_f32_e32 v133, v138
	v_pk_mul_f32 v[12:13], v[12:13], v[128:129]
	v_pk_mul_f32 v[14:15], v[14:15], v[130:131]
	v_pk_mul_f32 v[10:11], v[10:11], v[134:135]
	v_pk_mul_f32 v[8:9], v[8:9], v[132:133]
.LBB0_383:
	v_add_u32_e32 v141, 0xb0, v141
	v_mov_b64_e32 v[138:139], s[4:5]
	v_mad_i64_i32 v[138:139], s[2:3], v141, s14, v[138:139]
	v_lshl_add_u64 v[138:139], v[136:137], 1, v[138:139]
	v_cvt_pk_bf16_f32 v128, v12, v13
	v_cvt_pk_bf16_f32 v129, v14, v15
	v_cvt_pk_bf16_f32 v130, v8, v9
	v_cvt_pk_bf16_f32 v131, v10, v11
	global_store_dwordx4 v[138:139], v[128:131], off sc1 nt
	s_nop 0
	s_and_b64 vcc, exec, s[38:39]
	s_cbranch_vccnz .LBB0_385
	v_mul_f32_e32 v129, 0xbfb8aa3b, v0
	v_mul_f32_e32 v130, 0xbfb8aa3b, v5
	v_exp_f32_e32 v129, v129
	v_exp_f32_e32 v130, v130
	v_mul_f32_e32 v131, 0xbfb8aa3b, v6
	v_mul_f32_e32 v133, 0xbfb8aa3b, v2
	v_add_f32_e32 v129, 1.0, v129
	v_rcp_f32_e32 v132, v129
	v_add_f32_e32 v129, 1.0, v130
	v_mul_f32_e32 v130, 0xbfb8aa3b, v1
	v_exp_f32_e32 v130, v130
	v_exp_f32_e32 v131, v131
	v_exp_f32_e32 v133, v133
	v_mul_f32_e32 v128, 0xbfb8aa3b, v4
	v_add_f32_e32 v137, 1.0, v130
	v_add_f32_e32 v130, 1.0, v131
	v_add_f32_e32 v131, 1.0, v133
	v_mul_f32_e32 v133, 0xbfb8aa3b, v7
	v_mul_f32_e32 v134, 0xbfb8aa3b, v3
	v_exp_f32_e32 v128, v128
	v_exp_f32_e32 v133, v133
	v_exp_f32_e32 v135, v134
	v_rcp_f32_e32 v134, v131
	v_add_f32_e32 v128, 1.0, v128
	v_add_f32_e32 v131, 1.0, v133
	v_add_f32_e32 v133, 1.0, v135
	v_rcp_f32_e32 v128, v128
	v_rcp_f32_e32 v129, v129
	v_rcp_f32_e32 v130, v130
	v_rcp_f32_e32 v131, v131
	v_rcp_f32_e32 v135, v133
	v_rcp_f32_e32 v133, v137
	v_pk_mul_f32 v[4:5], v[4:5], v[128:129]
	v_pk_mul_f32 v[6:7], v[6:7], v[130:131]
	v_pk_mul_f32 v[2:3], v[2:3], v[134:135]
	v_pk_mul_f32 v[0:1], v[0:1], v[132:133]
.LBB0_385:
	v_cvt_pk_bf16_f32 v128, v4, v5
	v_cvt_pk_bf16_f32 v129, v6, v7
	v_cvt_pk_bf16_f32 v130, v0, v1
	v_cvt_pk_bf16_f32 v131, v2, v3
	global_store_dwordx4 v[138:139], v[128:131], off offset:256 sc1 nt
	s_branch .LBB0_352
